# prep-phase grid barrier: one monotonic counter (release/acquire by lane 0) instead of the cooperative-groups grid sync
# speedup vs baseline: 1.0243x; 1.0029x over previous
.LBB0_125:
	s_or_b64 exec, exec, s[4:5]
	v_readlane_b32 s8, v254, 8
	v_readlane_b32 s9, v254, 9
	s_cmp_lt_i32 s9, 2
	s_cbranch_scc1 .LBB0_137
	s_waitcnt vmcnt(0) lgkmcnt(0)
	s_barrier
	v_cmp_eq_u32_e32 vcc, 0, v144
	s_and_saveexec_b64 s[0:1], vcc
	s_cbranch_execz .Lp0bar_done
	buffer_wbl2 sc1
	s_waitcnt vmcnt(0)
	v_mov_b32_e32 v2, 0x1bf9c000
	v_mov_b32_e32 v3, 1
	global_atomic_add v2, v3, s[90:91] offset:1100
	v_readlane_b32 s2, v254, 10
.Lp0bar_spin:
	s_sleep 1
	global_load_dword v3, v2, s[90:91] offset:1100 sc1
	s_waitcnt vmcnt(0)
	v_readfirstlane_b32 s3, v3
	s_nop 1
	s_cmp_lt_u32 s3, s2
	s_cbranch_scc1 .Lp0bar_spin
	buffer_inv sc1
	s_waitcnt vmcnt(0)
